# phase_post rotary blocks: sign word and rotating-lane mask computed once per row, and the unread high-half sign xor dropped (43 blocks)
# baseline (speedup 1.0000x reference)
.LBB0_652:
	s_or_b64 exec, exec, s[0:1]
	ds_bpermute_b32 v5, v45, v97
	s_waitcnt lgkmcnt(2)
	ds_read_b64 v[2:3], v108 offset:8
	s_and_saveexec_b64 s[22:23], s[100:101]
	v_mov_b32_e32 v6, v97
	s_waitcnt lgkmcnt(0)
	v_mov_b32_e32 v7, v3
	v_mov_b32_e32 v4, v2
	v_mul_f32_e32 v56, v97, v2
	v_xor_b32_e32 v210, v208, v6
	v_xor_b32_e32 v211, v208, v7
	v_pk_fma_f32 v[4:5], v[210:211], v[4:5], v[56:57] op_sel_hi:[1,1,0]
	s_nop 0
	v_mov_b32_e32 v97, v5
	s_or_b64 exec, exec, s[22:23]
	s_waitcnt lgkmcnt(1)
	ds_bpermute_b32 v5, v45, v94
	ds_read_b64 v[6:7], v108 offset:16
	s_and_saveexec_b64 s[22:23], s[100:101]
	v_mov_b32_e32 v56, v94
	s_waitcnt lgkmcnt(0)
	v_mov_b32_e32 v57, v7
	v_mov_b32_e32 v4, v6
	v_mul_f32_e32 v58, v7, v5
	v_xor_b32_e32 v210, v208, v58
	v_pk_fma_f32 v[4:5], v[56:57], v[4:5], v[210:211] op_sel_hi:[1,1,0]
	s_nop 0
	v_mov_b32_e32 v94, v4
	s_or_b64 exec, exec, s[22:23]
	ds_bpermute_b32 v57, v45, v95
	s_waitcnt lgkmcnt(2)
	ds_read_b64 v[4:5], v108 offset:24
	s_and_saveexec_b64 s[22:23], s[100:101]
	v_mov_b32_e32 v58, v95
	s_waitcnt lgkmcnt(0)
	v_mov_b32_e32 v59, v5
	v_mov_b32_e32 v56, v4
	v_mul_f32_e32 v60, v5, v57
	v_xor_b32_e32 v210, v208, v60
	v_pk_fma_f32 v[56:57], v[58:59], v[56:57], v[210:211] op_sel_hi:[1,1,0]
	s_nop 0
	v_mov_b32_e32 v95, v56
	s_or_b64 exec, exec, s[22:23]
	s_waitcnt lgkmcnt(1)
	ds_bpermute_b32 v57, v45, v92
	ds_read_b64 v[58:59], v108 offset:32
	s_and_saveexec_b64 s[22:23], s[100:101]
	v_mov_b32_e32 v60, v92
	s_waitcnt lgkmcnt(0)
	v_mov_b32_e32 v61, v59
	v_mov_b32_e32 v56, v58
	v_mul_f32_e32 v62, v59, v57
	v_xor_b32_e32 v210, v208, v62
	v_pk_fma_f32 v[56:57], v[60:61], v[56:57], v[210:211] op_sel_hi:[1,1,0]
	s_nop 0
	v_mov_b32_e32 v92, v56
	s_or_b64 exec, exec, s[22:23]
	ds_bpermute_b32 v61, v45, v93
	s_waitcnt lgkmcnt(2)
	ds_read_b64 v[56:57], v108 offset:40
	s_and_saveexec_b64 s[22:23], s[100:101]
	v_mov_b32_e32 v62, v93
	s_waitcnt lgkmcnt(0)
	v_mov_b32_e32 v63, v57
	v_mov_b32_e32 v60, v56
	v_mul_f32_e32 v64, v57, v61
	v_xor_b32_e32 v210, v208, v64
	v_pk_fma_f32 v[60:61], v[62:63], v[60:61], v[210:211] op_sel_hi:[1,1,0]
	s_nop 0
	v_mov_b32_e32 v93, v60
	s_or_b64 exec, exec, s[22:23]
	s_waitcnt lgkmcnt(1)
	ds_bpermute_b32 v61, v45, v90
	ds_read_b64 v[62:63], v108 offset:48
	s_and_saveexec_b64 s[22:23], s[100:101]
	v_mov_b32_e32 v64, v90
	s_waitcnt lgkmcnt(0)
	v_mov_b32_e32 v65, v63
	v_mov_b32_e32 v60, v62
	v_mul_f32_e32 v66, v63, v61
	v_xor_b32_e32 v210, v208, v66
	v_pk_fma_f32 v[60:61], v[64:65], v[60:61], v[210:211] op_sel_hi:[1,1,0]
	s_nop 0
	v_mov_b32_e32 v90, v60
	s_or_b64 exec, exec, s[22:23]
	ds_bpermute_b32 v65, v45, v91
	s_waitcnt lgkmcnt(2)
	ds_read_b64 v[60:61], v108 offset:56
	s_and_saveexec_b64 s[22:23], s[100:101]
	v_mov_b32_e32 v66, v91
	s_waitcnt lgkmcnt(0)
	v_mov_b32_e32 v67, v61
	v_mov_b32_e32 v64, v60
	v_mul_f32_e32 v68, v61, v65
	v_xor_b32_e32 v210, v208, v68
	v_pk_fma_f32 v[64:65], v[66:67], v[64:65], v[210:211] op_sel_hi:[1,1,0]
	s_nop 0
	v_mov_b32_e32 v91, v64
	s_or_b64 exec, exec, s[22:23]
	s_waitcnt lgkmcnt(1)
	ds_bpermute_b32 v65, v45, v88
	ds_read_b64 v[66:67], v108 offset:64
	s_and_saveexec_b64 s[22:23], s[100:101]
	v_mov_b32_e32 v68, v88
	s_waitcnt lgkmcnt(0)
	v_mov_b32_e32 v69, v67
	v_mov_b32_e32 v64, v66
	v_mul_f32_e32 v70, v67, v65
	v_xor_b32_e32 v210, v208, v70
	v_pk_fma_f32 v[64:65], v[68:69], v[64:65], v[210:211] op_sel_hi:[1,1,0]
	s_nop 0
	v_mov_b32_e32 v88, v64
	s_or_b64 exec, exec, s[22:23]
	ds_bpermute_b32 v69, v45, v89
	s_waitcnt lgkmcnt(2)
	ds_read_b64 v[64:65], v108 offset:72
	s_and_saveexec_b64 s[22:23], s[100:101]
	v_mov_b32_e32 v70, v89
	s_waitcnt lgkmcnt(0)
	v_mov_b32_e32 v71, v65
	v_mov_b32_e32 v68, v64
	v_mul_f32_e32 v72, v65, v69
	v_xor_b32_e32 v210, v208, v72
	v_pk_fma_f32 v[68:69], v[70:71], v[68:69], v[210:211] op_sel_hi:[1,1,0]
	s_nop 0
	v_mov_b32_e32 v89, v68
	s_or_b64 exec, exec, s[22:23]
	s_waitcnt lgkmcnt(1)
	ds_bpermute_b32 v69, v45, v86
	ds_read_b64 v[70:71], v108 offset:80
	s_and_saveexec_b64 s[22:23], s[100:101]
	v_mov_b32_e32 v72, v86
	s_waitcnt lgkmcnt(0)
	v_mov_b32_e32 v73, v71
	v_mov_b32_e32 v68, v70
	v_mul_f32_e32 v74, v71, v69
	v_xor_b32_e32 v210, v208, v74
	v_pk_fma_f32 v[68:69], v[72:73], v[68:69], v[210:211] op_sel_hi:[1,1,0]
	s_nop 0
	v_mov_b32_e32 v86, v68
	s_or_b64 exec, exec, s[22:23]
	ds_bpermute_b32 v73, v45, v87
	s_waitcnt lgkmcnt(2)
	ds_read_b64 v[68:69], v108 offset:88
	s_and_saveexec_b64 s[22:23], s[100:101]
	v_mov_b32_e32 v74, v87
	s_waitcnt lgkmcnt(0)
	v_mov_b32_e32 v75, v69
	v_mov_b32_e32 v72, v68
	v_mul_f32_e32 v76, v69, v73
	v_xor_b32_e32 v210, v208, v76
	v_pk_fma_f32 v[72:73], v[74:75], v[72:73], v[210:211] op_sel_hi:[1,1,0]
	s_nop 0
	v_mov_b32_e32 v87, v72
	s_or_b64 exec, exec, s[22:23]
	s_waitcnt lgkmcnt(1)
	ds_bpermute_b32 v73, v45, v84
	ds_read_b64 v[74:75], v108 offset:96
	s_and_saveexec_b64 s[22:23], s[100:101]
	v_mov_b32_e32 v76, v84
	s_waitcnt lgkmcnt(0)
	v_mov_b32_e32 v77, v75
	v_mov_b32_e32 v72, v74
	v_mul_f32_e32 v78, v75, v73
	v_xor_b32_e32 v210, v208, v78
	v_pk_fma_f32 v[72:73], v[76:77], v[72:73], v[210:211] op_sel_hi:[1,1,0]
	s_nop 0
	v_mov_b32_e32 v84, v72
	s_or_b64 exec, exec, s[22:23]
	ds_bpermute_b32 v77, v45, v85
	s_waitcnt lgkmcnt(2)
	ds_read_b64 v[72:73], v108 offset:104
	s_and_saveexec_b64 s[22:23], s[100:101]
	v_mov_b32_e32 v78, v85
	s_waitcnt lgkmcnt(0)
	v_mov_b32_e32 v79, v73
	v_mov_b32_e32 v76, v72
	v_mul_f32_e32 v98, v73, v77
	v_xor_b32_e32 v210, v208, v98
	v_pk_fma_f32 v[76:77], v[78:79], v[76:77], v[210:211] op_sel_hi:[1,1,0]
	s_nop 0
	v_mov_b32_e32 v85, v76
	s_or_b64 exec, exec, s[22:23]
	s_waitcnt lgkmcnt(1)
	ds_bpermute_b32 v77, v45, v82
	ds_read_b64 v[78:79], v108 offset:112
	s_and_saveexec_b64 s[22:23], s[100:101]
	v_mov_b32_e32 v98, v82
	s_waitcnt lgkmcnt(0)
	v_mov_b32_e32 v99, v79
	v_mov_b32_e32 v76, v78
	v_mul_f32_e32 v82, v79, v77
	v_xor_b32_e32 v210, v208, v82
	v_pk_fma_f32 v[76:77], v[98:99], v[76:77], v[210:211] op_sel_hi:[1,1,0]
	s_nop 0
	v_mov_b32_e32 v82, v76
	s_or_b64 exec, exec, s[22:23]
	ds_bpermute_b32 v99, v45, v83
	s_waitcnt lgkmcnt(2)
	ds_read_b64 v[76:77], v108 offset:120
	s_and_saveexec_b64 s[22:23], s[100:101]
	v_mov_b32_e32 v100, v83
	s_waitcnt lgkmcnt(0)
	v_mov_b32_e32 v101, v77
	v_mov_b32_e32 v98, v76
	v_mul_f32_e32 v102, v77, v99
	v_xor_b32_e32 v210, v208, v102
	v_pk_fma_f32 v[98:99], v[100:101], v[98:99], v[210:211] op_sel_hi:[1,1,0]
	s_nop 0
	v_mov_b32_e32 v83, v98
	s_or_b64 exec, exec, s[22:23]
	v_cvt_pk_bf16_f32 v96, v96, v97
	v_cvt_pk_bf16_f32 v97, v94, v95
	v_cvt_pk_bf16_f32 v98, v92, v93
	s_waitcnt lgkmcnt(1)
	v_cvt_pk_bf16_f32 v99, v90, v91
	v_cvt_pk_bf16_f32 v88, v88, v89
	v_cvt_pk_bf16_f32 v89, v86, v87
	v_cvt_pk_bf16_f32 v90, v84, v85
	v_cvt_pk_bf16_f32 v91, v82, v83
	global_store_dwordx4 v[80:81], v[96:99], off
	global_store_dwordx4 v[80:81], v[88:91], off offset:16
	v_lshlrev_b64 v[80:81], 8, v[42:43]
	v_lshl_add_u64 v[80:81], v[50:51], 0, v[80:81]
	v_mov_b32_e32 v90, 0
	v_mov_b32_e32 v91, 0
	v_mov_b32_e32 v82, 0
	v_mov_b32_e32 v83, 0
	v_mov_b32_e32 v84, 0
	v_mov_b32_e32 v85, 0
	v_mov_b32_e32 v86, 0
	v_mov_b32_e32 v87, 0
	v_mov_b32_e32 v88, 0
	v_mov_b32_e32 v89, 0
	v_mov_b32_e32 v100, 0
	v_mov_b32_e32 v101, 0
	v_mov_b32_e32 v102, 0
	v_mov_b32_e32 v103, 0
	v_mov_b32_e32 v104, 0
	v_mov_b32_e32 v105, 0
	s_and_saveexec_b64 s[0:1], s[4:5]
	s_cbranch_execz .LBB0_744
	v_mov_b32_e32 v84, v184
	v_mov_b32_e32 v85, v185
	v_mov_b32_e32 v86, v186
	v_mov_b32_e32 v87, v187
	v_mov_b32_e32 v92, v188
	v_mov_b32_e32 v93, v189
	v_mov_b32_e32 v94, v190
	v_mov_b32_e32 v95, v191
	v_lshlrev_b32_e32 v90, 16, v84
	v_and_b32_e32 v91, 0xffff0000, v84
	v_lshlrev_b32_e32 v82, 16, v85
	v_and_b32_e32 v83, 0xffff0000, v85
	v_lshlrev_b32_e32 v84, 16, v86
	v_and_b32_e32 v85, 0xffff0000, v86
	v_lshlrev_b32_e32 v86, 16, v87
	v_and_b32_e32 v87, 0xffff0000, v87
	v_lshlrev_b32_e32 v88, 16, v92
	v_and_b32_e32 v89, 0xffff0000, v92
	v_lshlrev_b32_e32 v100, 16, v93
	v_and_b32_e32 v101, 0xffff0000, v93
	v_lshlrev_b32_e32 v102, 16, v94
	v_and_b32_e32 v103, 0xffff0000, v94
	v_lshlrev_b32_e32 v104, 16, v95
	v_and_b32_e32 v105, 0xffff0000, v95

.LBB0_750:
	s_or_b64 exec, exec, s[0:1]
	ds_bpermute_b32 v1, v45, v97
	s_and_saveexec_b64 s[22:23], s[100:101]
	v_mov_b32_e32 v0, v97
	v_mul_f32_e32 v98, v2, v97
	s_waitcnt lgkmcnt(0)
	v_xor_b32_e32 v210, v208, v2
	v_xor_b32_e32 v211, v208, v3
	v_pk_fma_f32 v[0:1], v[210:211], v[0:1], v[98:99] op_sel_hi:[1,1,0]
	s_nop 0
	v_mov_b32_e32 v97, v1
	s_or_b64 exec, exec, s[22:23]
	s_waitcnt lgkmcnt(0)
	ds_bpermute_b32 v1, v45, v94
	s_and_saveexec_b64 s[22:23], s[100:101]
	v_mov_b32_e32 v0, v94
	s_waitcnt lgkmcnt(0)
	v_mul_f32_e32 v2, v7, v1
	v_xor_b32_e32 v210, v208, v2
	v_pk_fma_f32 v[0:1], v[6:7], v[0:1], v[210:211] op_sel_hi:[1,1,0]
	s_nop 0
	v_mov_b32_e32 v94, v0
	s_or_b64 exec, exec, s[22:23]
	s_waitcnt lgkmcnt(0)
	ds_bpermute_b32 v1, v45, v95
	s_and_saveexec_b64 s[22:23], s[100:101]
	v_mov_b32_e32 v0, v95
	s_waitcnt lgkmcnt(0)
	v_mul_f32_e32 v2, v5, v1
	v_xor_b32_e32 v210, v208, v2
	v_pk_fma_f32 v[0:1], v[4:5], v[0:1], v[210:211] op_sel_hi:[1,1,0]
	s_nop 0
	v_mov_b32_e32 v95, v0
	s_or_b64 exec, exec, s[22:23]
	s_waitcnt lgkmcnt(0)
	ds_bpermute_b32 v1, v45, v92
	s_and_saveexec_b64 s[22:23], s[100:101]
	v_mov_b32_e32 v0, v92
	s_waitcnt lgkmcnt(0)
	v_mul_f32_e32 v2, v59, v1
	v_xor_b32_e32 v210, v208, v2
	v_pk_fma_f32 v[0:1], v[58:59], v[0:1], v[210:211] op_sel_hi:[1,1,0]
	s_nop 0
	v_mov_b32_e32 v92, v0
	s_or_b64 exec, exec, s[22:23]
	s_waitcnt lgkmcnt(0)
	ds_bpermute_b32 v1, v45, v93
	s_and_saveexec_b64 s[22:23], s[100:101]
	v_mov_b32_e32 v0, v93
	s_waitcnt lgkmcnt(0)
	v_mul_f32_e32 v2, v57, v1
	v_xor_b32_e32 v210, v208, v2
	v_pk_fma_f32 v[0:1], v[56:57], v[0:1], v[210:211] op_sel_hi:[1,1,0]
	s_nop 0
	v_mov_b32_e32 v93, v0
	s_or_b64 exec, exec, s[22:23]
	s_waitcnt lgkmcnt(0)
	ds_bpermute_b32 v1, v45, v90
	s_and_saveexec_b64 s[22:23], s[100:101]
	v_mov_b32_e32 v0, v90
	s_waitcnt lgkmcnt(0)
	v_mul_f32_e32 v2, v63, v1
	v_xor_b32_e32 v210, v208, v2
	v_pk_fma_f32 v[0:1], v[62:63], v[0:1], v[210:211] op_sel_hi:[1,1,0]
	s_nop 0
	v_mov_b32_e32 v90, v0
	s_or_b64 exec, exec, s[22:23]
	s_waitcnt lgkmcnt(0)
	ds_bpermute_b32 v1, v45, v91
	s_and_saveexec_b64 s[22:23], s[100:101]
	v_mov_b32_e32 v0, v91
	s_waitcnt lgkmcnt(0)
	v_mul_f32_e32 v2, v61, v1
	v_xor_b32_e32 v210, v208, v2
	v_pk_fma_f32 v[0:1], v[60:61], v[0:1], v[210:211] op_sel_hi:[1,1,0]
	s_nop 0
	v_mov_b32_e32 v91, v0
	s_or_b64 exec, exec, s[22:23]
	s_waitcnt lgkmcnt(0)
	ds_bpermute_b32 v1, v45, v88
	s_and_saveexec_b64 s[22:23], s[100:101]
	v_mov_b32_e32 v0, v88
	s_waitcnt lgkmcnt(0)
	v_mul_f32_e32 v2, v67, v1
	v_xor_b32_e32 v210, v208, v2
	v_pk_fma_f32 v[0:1], v[66:67], v[0:1], v[210:211] op_sel_hi:[1,1,0]
	s_nop 0
	v_mov_b32_e32 v88, v0
	s_or_b64 exec, exec, s[22:23]
	s_waitcnt lgkmcnt(0)
	ds_bpermute_b32 v1, v45, v89
	s_and_saveexec_b64 s[22:23], s[100:101]
	v_mov_b32_e32 v0, v89
	s_waitcnt lgkmcnt(0)
	v_mul_f32_e32 v2, v65, v1
	v_xor_b32_e32 v210, v208, v2
	v_pk_fma_f32 v[0:1], v[64:65], v[0:1], v[210:211] op_sel_hi:[1,1,0]
	s_nop 0
	v_mov_b32_e32 v89, v0
	s_or_b64 exec, exec, s[22:23]
	s_waitcnt lgkmcnt(0)
	ds_bpermute_b32 v1, v45, v86
	s_and_saveexec_b64 s[22:23], s[100:101]
	v_mov_b32_e32 v0, v86
	s_waitcnt lgkmcnt(0)
	v_mul_f32_e32 v2, v71, v1
	v_xor_b32_e32 v210, v208, v2
	v_pk_fma_f32 v[0:1], v[70:71], v[0:1], v[210:211] op_sel_hi:[1,1,0]
	s_nop 0
	v_mov_b32_e32 v86, v0
	s_or_b64 exec, exec, s[22:23]
	s_waitcnt lgkmcnt(0)
	ds_bpermute_b32 v1, v45, v87
	s_and_saveexec_b64 s[22:23], s[100:101]
	v_mov_b32_e32 v0, v87
	s_waitcnt lgkmcnt(0)
	v_mul_f32_e32 v2, v69, v1
	v_xor_b32_e32 v210, v208, v2
	v_pk_fma_f32 v[0:1], v[68:69], v[0:1], v[210:211] op_sel_hi:[1,1,0]
	s_nop 0
	v_mov_b32_e32 v87, v0
	s_or_b64 exec, exec, s[22:23]
	s_waitcnt lgkmcnt(0)
	ds_bpermute_b32 v1, v45, v84
	s_and_saveexec_b64 s[22:23], s[100:101]
	v_mov_b32_e32 v0, v84
	s_waitcnt lgkmcnt(0)
	v_mul_f32_e32 v2, v75, v1
	v_xor_b32_e32 v210, v208, v2
	v_pk_fma_f32 v[0:1], v[74:75], v[0:1], v[210:211] op_sel_hi:[1,1,0]
	s_nop 0
	v_mov_b32_e32 v84, v0
	s_or_b64 exec, exec, s[22:23]
	s_waitcnt lgkmcnt(0)
	ds_bpermute_b32 v1, v45, v85
	s_and_saveexec_b64 s[22:23], s[100:101]
	v_mov_b32_e32 v0, v85
	s_waitcnt lgkmcnt(0)
	v_mul_f32_e32 v2, v73, v1
	v_xor_b32_e32 v210, v208, v2
	v_pk_fma_f32 v[0:1], v[72:73], v[0:1], v[210:211] op_sel_hi:[1,1,0]
	s_nop 0
	v_mov_b32_e32 v85, v0
	s_or_b64 exec, exec, s[22:23]
	s_waitcnt lgkmcnt(0)
	ds_bpermute_b32 v1, v45, v82
	s_and_saveexec_b64 s[22:23], s[100:101]
	v_mov_b32_e32 v0, v82
	s_waitcnt lgkmcnt(0)
	v_mul_f32_e32 v2, v79, v1
	v_xor_b32_e32 v210, v208, v2
	v_pk_fma_f32 v[0:1], v[78:79], v[0:1], v[210:211] op_sel_hi:[1,1,0]
	s_nop 0
	v_mov_b32_e32 v82, v0
	s_or_b64 exec, exec, s[22:23]
	s_waitcnt lgkmcnt(0)
	ds_bpermute_b32 v1, v45, v83
	v_cmp_lt_i32_e64 s[0:1], 0, v16
	s_and_saveexec_b64 s[22:23], s[0:1]
	s_xor_b64 s[22:23], exec, s[22:23]
	s_cbranch_execz .LBB0_937
	v_cmp_eq_u32_e64 s[0:1], 1, v16
	s_and_saveexec_b64 s[24:25], s[0:1]
	s_cbranch_execz .LBB0_837
	v_mov_b32_e32 v0, v83
	s_waitcnt lgkmcnt(0)
	v_mul_f32_e32 v2, v77, v1
	v_pk_fma_f32 v[0:1], v[76:77], v[0:1], v[2:3] op_sel_hi:[1,1,0]
	s_nop 0
	v_mov_b32_e32 v83, v0

.LBB0_846:
	s_or_b64 exec, exec, s[0:1]
	ds_bpermute_b32 v63, v45, v1
	v_mov_b32_e32 v0, v60
	s_waitcnt lgkmcnt(1)
	ds_read_b64 v[60:61], v108 offset:136
	s_and_saveexec_b64 s[22:23], s[100:101]
	v_mov_b32_e32 v64, v1
	s_waitcnt lgkmcnt(0)
	v_mov_b32_e32 v65, v61
	v_mov_b32_e32 v62, v60
	v_mul_f32_e32 v66, v1, v60
	v_xor_b32_e32 v210, v208, v64
	v_xor_b32_e32 v211, v208, v65
	v_pk_fma_f32 v[62:63], v[210:211], v[62:63], v[66:67] op_sel_hi:[1,1,0]
	s_nop 0
	v_mov_b32_e32 v1, v63
	s_or_b64 exec, exec, s[22:23]
	s_waitcnt lgkmcnt(1)
	ds_bpermute_b32 v63, v45, v2
	ds_read_b64 v[64:65], v108 offset:144
	s_and_saveexec_b64 s[22:23], s[100:101]
	v_mov_b32_e32 v66, v2
	s_waitcnt lgkmcnt(0)
	v_mov_b32_e32 v67, v65
	v_mov_b32_e32 v62, v64
	v_mul_f32_e32 v2, v65, v63
	v_xor_b32_e32 v210, v208, v2
	v_pk_fma_f32 v[62:63], v[66:67], v[62:63], v[210:211] op_sel_hi:[1,1,0]
	s_nop 0
	v_mov_b32_e32 v2, v62
	s_or_b64 exec, exec, s[22:23]
	ds_bpermute_b32 v67, v45, v3
	s_waitcnt lgkmcnt(2)
	ds_read_b64 v[62:63], v108 offset:152
	s_and_saveexec_b64 s[22:23], s[100:101]
	v_mov_b32_e32 v68, v3
	s_waitcnt lgkmcnt(0)
	v_mov_b32_e32 v69, v63
	v_mov_b32_e32 v66, v62
	v_mul_f32_e32 v70, v63, v67
	v_xor_b32_e32 v210, v208, v70
	v_pk_fma_f32 v[66:67], v[68:69], v[66:67], v[210:211] op_sel_hi:[1,1,0]
	s_nop 0
	v_mov_b32_e32 v3, v66
	s_or_b64 exec, exec, s[22:23]
	s_waitcnt lgkmcnt(1)
	ds_bpermute_b32 v67, v45, v4
	ds_read_b64 v[68:69], v108 offset:160
	s_and_saveexec_b64 s[22:23], s[100:101]
	v_mov_b32_e32 v70, v4
	s_waitcnt lgkmcnt(0)
	v_mov_b32_e32 v71, v69
	v_mov_b32_e32 v66, v68
	v_mul_f32_e32 v4, v69, v67
	v_xor_b32_e32 v210, v208, v4
	v_pk_fma_f32 v[66:67], v[70:71], v[66:67], v[210:211] op_sel_hi:[1,1,0]
	s_nop 0
	v_mov_b32_e32 v4, v66
	s_or_b64 exec, exec, s[22:23]
	ds_bpermute_b32 v71, v45, v5
	s_waitcnt lgkmcnt(2)
	ds_read_b64 v[66:67], v108 offset:168
	s_and_saveexec_b64 s[22:23], s[100:101]
	v_mov_b32_e32 v72, v5
	s_waitcnt lgkmcnt(0)
	v_mov_b32_e32 v73, v67
	v_mov_b32_e32 v70, v66
	v_mul_f32_e32 v74, v67, v71
	v_xor_b32_e32 v210, v208, v74
	v_pk_fma_f32 v[70:71], v[72:73], v[70:71], v[210:211] op_sel_hi:[1,1,0]
	s_nop 0
	v_mov_b32_e32 v5, v70
	s_or_b64 exec, exec, s[22:23]
	s_waitcnt lgkmcnt(1)
	ds_bpermute_b32 v71, v45, v6
	ds_read_b64 v[72:73], v108 offset:176
	s_and_saveexec_b64 s[22:23], s[100:101]
	v_mov_b32_e32 v74, v6
	s_waitcnt lgkmcnt(0)
	v_mov_b32_e32 v75, v73
	v_mov_b32_e32 v70, v72
	v_mul_f32_e32 v6, v73, v71
	v_xor_b32_e32 v210, v208, v6
	v_pk_fma_f32 v[70:71], v[74:75], v[70:71], v[210:211] op_sel_hi:[1,1,0]
	s_nop 0
	v_mov_b32_e32 v6, v70
	s_or_b64 exec, exec, s[22:23]
	ds_bpermute_b32 v75, v45, v7
	s_waitcnt lgkmcnt(2)
	ds_read_b64 v[70:71], v108 offset:184
	s_and_saveexec_b64 s[22:23], s[100:101]
	v_mov_b32_e32 v76, v7
	s_waitcnt lgkmcnt(0)
	v_mov_b32_e32 v77, v71
	v_mov_b32_e32 v74, v70
	v_mul_f32_e32 v78, v71, v75
	v_xor_b32_e32 v210, v208, v78
	v_pk_fma_f32 v[74:75], v[76:77], v[74:75], v[210:211] op_sel_hi:[1,1,0]
	s_nop 0
	v_mov_b32_e32 v7, v74
	s_or_b64 exec, exec, s[22:23]
	v_cvt_pk_bf16_f32 v0, v0, v1
	v_cvt_pk_bf16_f32 v1, v2, v3
	v_cvt_pk_bf16_f32 v2, v4, v5
	v_cvt_pk_bf16_f32 v3, v6, v7
	global_store_dwordx4 v[58:59], v[0:3], off
	s_nop 1
	v_lshlrev_b64 v[0:1], 7, v[42:43]
	v_lshl_add_u64 v[58:59], v[54:55], 0, v[0:1]
	v_mov_b32_e32 v0, 0
	v_mov_b32_e32 v1, v0
	v_mov_b32_e32 v2, v0
	v_mov_b32_e32 v3, v0
	v_mov_b32_e32 v4, v0
	v_mov_b32_e32 v5, v0
	v_mov_b32_e32 v6, v0
	v_mov_b32_e32 v7, v0
	s_and_saveexec_b64 s[0:1], s[4:5]
	s_cbranch_execz .LBB0_890
	v_mov_b32_e32 v4, v196
	v_mov_b32_e32 v5, v197
	v_mov_b32_e32 v6, v198
	v_mov_b32_e32 v7, v199
	v_lshlrev_b32_e32 v0, 16, v4
	v_and_b32_e32 v1, 0xffff0000, v4
	v_lshlrev_b32_e32 v2, 16, v5
	v_and_b32_e32 v3, 0xffff0000, v5
	v_lshlrev_b32_e32 v4, 16, v6
	v_and_b32_e32 v5, 0xffff0000, v6
	v_lshlrev_b32_e32 v6, 16, v7
	v_and_b32_e32 v7, 0xffff0000, v7
.LBB0_890:
	s_or_b64 exec, exec, s[0:1]
	s_waitcnt lgkmcnt(1)
	ds_bpermute_b32 v75, v45, v0
	s_and_saveexec_b64 s[22:23], s[100:101]
	v_mov_b32_e32 v74, v0
	s_waitcnt lgkmcnt(0)
	v_pk_mul_f32 v[56:57], v[56:57], v[74:75]
	s_nop 0
	v_xor_b32_e32 v210, v208, v57
	v_add_f32_e32 v0, v56, v210
	s_or_b64 exec, exec, s[22:23]
	ds_bpermute_b32 v57, v45, v1
	s_and_saveexec_b64 s[22:23], s[100:101]
	v_mov_b32_e32 v56, v1
	v_mul_f32_e32 v74, v60, v1
	s_waitcnt lgkmcnt(0)
	v_xor_b32_e32 v210, v208, v60
	v_xor_b32_e32 v211, v208, v61
	v_pk_fma_f32 v[56:57], v[210:211], v[56:57], v[74:75] op_sel_hi:[1,1,0]
	s_nop 0
	v_mov_b32_e32 v1, v57
	s_or_b64 exec, exec, s[22:23]
	s_waitcnt lgkmcnt(0)
	ds_bpermute_b32 v57, v45, v2
	s_and_saveexec_b64 s[22:23], s[100:101]
	v_mov_b32_e32 v56, v2
	s_waitcnt lgkmcnt(0)
	v_mul_f32_e32 v2, v65, v57
	v_xor_b32_e32 v210, v208, v2
	v_pk_fma_f32 v[56:57], v[64:65], v[56:57], v[210:211] op_sel_hi:[1,1,0]
	s_nop 0
	v_mov_b32_e32 v2, v56
	s_or_b64 exec, exec, s[22:23]
	s_waitcnt lgkmcnt(0)
	ds_bpermute_b32 v57, v45, v3
	s_and_saveexec_b64 s[22:23], s[100:101]
	v_mov_b32_e32 v56, v3
	s_waitcnt lgkmcnt(0)
	v_mul_f32_e32 v60, v63, v57
	v_xor_b32_e32 v210, v208, v60
	v_pk_fma_f32 v[56:57], v[62:63], v[56:57], v[210:211] op_sel_hi:[1,1,0]
	s_nop 0
	v_mov_b32_e32 v3, v56
	s_or_b64 exec, exec, s[22:23]
	s_waitcnt lgkmcnt(0)
	ds_bpermute_b32 v57, v45, v4
	s_and_saveexec_b64 s[22:23], s[100:101]
	v_mov_b32_e32 v56, v4
	s_waitcnt lgkmcnt(0)
	v_mul_f32_e32 v4, v69, v57
	v_xor_b32_e32 v210, v208, v4
	v_pk_fma_f32 v[56:57], v[68:69], v[56:57], v[210:211] op_sel_hi:[1,1,0]
	s_nop 0
	v_mov_b32_e32 v4, v56
	s_or_b64 exec, exec, s[22:23]
	s_waitcnt lgkmcnt(0)
	ds_bpermute_b32 v57, v45, v5
	s_and_saveexec_b64 s[22:23], s[100:101]
	v_mov_b32_e32 v56, v5
	s_waitcnt lgkmcnt(0)
	v_mul_f32_e32 v60, v67, v57
	v_xor_b32_e32 v210, v208, v60
	v_pk_fma_f32 v[56:57], v[66:67], v[56:57], v[210:211] op_sel_hi:[1,1,0]
	s_nop 0
	v_mov_b32_e32 v5, v56
	s_or_b64 exec, exec, s[22:23]
	s_waitcnt lgkmcnt(0)
	ds_bpermute_b32 v57, v45, v6
	s_and_saveexec_b64 s[22:23], s[100:101]
	v_mov_b32_e32 v56, v6
	s_waitcnt lgkmcnt(0)
	v_mul_f32_e32 v6, v73, v57
	v_xor_b32_e32 v210, v208, v6
	v_pk_fma_f32 v[56:57], v[72:73], v[56:57], v[210:211] op_sel_hi:[1,1,0]
	s_nop 0
	v_mov_b32_e32 v6, v56
	s_or_b64 exec, exec, s[22:23]
	s_waitcnt lgkmcnt(0)
	ds_bpermute_b32 v57, v45, v7
	v_cmp_lt_i32_e64 s[0:1], 0, v16
	s_and_saveexec_b64 s[22:23], s[0:1]
	s_xor_b64 s[22:23], exec, s[22:23]
	s_cbranch_execz .LBB0_939
	v_cmp_eq_u32_e64 s[0:1], 1, v16
	s_and_saveexec_b64 s[24:25], s[0:1]
	s_cbranch_execz .LBB0_935
	v_mov_b32_e32 v56, v7
	s_waitcnt lgkmcnt(0)
	v_mul_f32_e32 v60, v71, v57
	v_pk_fma_f32 v[56:57], v[70:71], v[56:57], v[60:61] op_sel_hi:[1,1,0]
	s_nop 0
	v_mov_b32_e32 v7, v56
